# P1: round-2 tiles swapped between WG halves so every workgroup gets one gelu epilogue; dtype comment at top
# speedup vs baseline: 1.0063x; 1.0017x over previous
;     __device__ __forceinline__ bool next(int i, Unit& u) const {
;     ...
;             const int L = i * G + c, n0 = nM0 * nN0;
;             if (L < n0) { swz_tile(L, nM0, nN0, pm, pn); u.pm = pm; u.pn = pn; u.kind = 0; u.A = A0 + (size_t)pm * tstep; u.B = B0 + (size_t)pn * tstep; return true; }
;             const int L1 = L - n0; if (L1 >= nM1 * nN1) return false;
.LBB0_99:
	s_add_i32 s29, s29, 1
	v_readlane_b32 s48, v247, 29
	s_mul_i32 s1, s29, s48
	s_add_i32 s1, s1, s63
	s_cmp_eq_u32 s29, 2
	s_cselect_b32 s98, 0x80, 0
	s_cmp_eq_u32 s48, 0x100
	s_cselect_b32 s98, s98, 0
	s_xor_b32 s1, s1, s98
	s_cmpk_gt_i32 s1, 0x3ff
	v_readlane_b32 s49, v247, 30
	s_cbranch_scc0 .LBB0_111
	s_and_b32 s3, s1, 0x7fffff00
	s_mov_b64 s[48:49], 0
	s_cmpk_eq_i32 s3, 0x400
	s_mov_b64 s[56:57], 0
	s_cbranch_scc1 .LBB0_119
	s_mov_b64 s[58:59], 0x3800000
	s_and_b64 vcc, exec, s[48:49]
	s_cbranch_vccnz .LBB0_120
